# NSA preheader: first two selection tiles fetched together + L2 warm-up of rotated Q / first tile before top-k; weight-transpose filler items handle 4 consecutive tiles per queue item (all row loads in
# speedup vs baseline: 1.0815x; 1.0074x over previous
; DI void xpose_tile(int wv0, PP p, int jt, unsigned char* smem) {
;     ...
;   if (t < 1024) { src = p->w_in; dst = (u16*)(p->ws + OFF_WINT); K = 1024; Nsrc = 3864; mode = 1; }
;   else if ((t -= 1024) < 128) { src = p->kw1; dst = (u16*)(p->ws + OFF_W1KT); K = 2048; Nsrc = 256; }
;   else if ((t -= 128) < 128) { src = p->vw1; dst = (u16*)(p->ws + OFF_W1VT); K = 2048; Nsrc = 256; }
;   else if ((t -= 128) < 16) { src = p->kw2; dst = (u16*)(p->ws + OFF_W2KT); K = 256; Nsrc = 64; mode = 2; }
;   else if ((t -= 16) < 16) { src = p->vw2; dst = (u16*)(p->ws + OFF_W2VT); K = 256; Nsrc = 64; mode = 2; }
;   else if ((t -= 16) < 128) { src = p->w_attn; dst = (u16*)(p->ws + OFF_WAT); K = 512; Nsrc = 1024; }
;   else if ((t -= 128) < 128) { src = p->w_val; dst = (u16*)(p->ws + OFF_WVT); K = 512; Nsrc = 1024; rowil = 0; }
;   else if ((t -= 128) < 128) { src = p->w_gate; dst = (u16*)(p->ws + OFF_WVT); K = 512; Nsrc = 1024; rowil = 128; }
;   else if ((t -= 128) < 256) { src = p->w_out; dst = (u16*)(p->ws + OFF_WOT); K = 1024; Nsrc = 1024; }
;   else if ((t -= 256) < 1024) { src = p->w_up; dst = (u16*)(p->ws + OFF_WUPT); K = 1024; Nsrc = 4096; scl = p->g2; }
;   else { t -= 1024; src = p->w_down; dst = (u16*)(p->ws + OFF_WDT); K = 4096; Nsrc = 1024; }
; DI void phaseE(int wv0, PP p, unsigned char* smem, int cidx) {
;     ...
;   for (;;) {
;     __syncthreads();
;     if (my_tid(wv0) == 0) s_item = atomicAdd(ctr, 1);
;     __syncthreads();
;     const int item = s_item;
;     if (item >= 1024 + 2048 + (NXT - NXT_A)) break;
;     if (item < 1024) nsa_item(wv0, p, item, smem);
;     else if (item < 1024 + 2048) s5_item<true>(wv0, p, item - 1024, smem);
;     else xpose_tile(wv0, p, NXT_A + (item - 3072), smem);
.LBB0_730:
	s_or_b64 exec, exec, s[2:3]
	s_waitcnt lgkmcnt(0)
	s_barrier
	ds_read_b32 v0, v1 offset:16
	s_movk_i32 s2, 0xe9f
	s_waitcnt lgkmcnt(0)
	v_cmp_lt_i32_e32 vcc, s2, v0
	v_readfirstlane_b32 s16, v0
	s_mov_b64 s[2:3], -1
	s_cbranch_vccnz .LBB0_725
	s_cmpk_gt_i32 s16, 0x3ff
	s_cbranch_scc0 .LBB0_792
	s_cmpk_gt_u32 s16, 0xbff
	s_cbranch_scc0 .LBB0_758
	s_lshl_b32 s16, s16, 2
	s_add_i32 s16, s16, 0xffffdc00
	s_add_i32 s15, s16, 0xfffff920
	v_mov_b32_e32 v6, v137
	s_cmpk_gt_u32 s15, 0x59f
	s_mov_b64 s[12:13], -1
	s_cbranch_scc0 .LBB0_750
	s_cmpk_gt_u32 s15, 0x61f
	s_cbranch_scc0 .LBB0_747
	s_mov_b64 s[2:3], -1
	s_cmpk_gt_u32 s15, 0x69f
	s_cbranch_scc0 .LBB0_744
	s_cmpk_gt_u32 s15, 0x79f
	s_cbranch_scc0 .LBB0_741
	s_cmpk_gt_u32 s15, 0xb9f
	s_mov_b64 s[4:5], -1
	s_cbranch_scc0 .LBB0_739
	s_add_i32 s14, s16, 0xffffed80
	s_mov_b64 s[4:5], 0

; DI void xpose_tile(int wv0, PP p, int jt, unsigned char* smem) {
;     ...
;   for (int kk = ty; kk < 64; kk += 8) {
;     float val = 0.f;
;     if (sc >= 0) val = src[(size_t)(k0 + kk) * Nsrc + sc];
;     if (scl) val *= scl[k0 + kk];
;     tile[kk * 65 + tx] = val;
;   }
.LBB0_752:
	s_lshr_b32 s12, s17, 6
	s_ff1_i32_b32 s13, s12
	s_add_i32 s12, s12, -1
	s_lshr_b32 s13, s14, s13
	s_and_b32 s12, s14, s12
	s_and_b32 s13, s13, 0xffff
	s_lshl_b32 s12, s12, 6
	v_ashrrev_i32_e32 v0, 6, v6
	s_lshl_b32 s20, s13, 6
	s_and_b32 s19, s12, 0x3fffc0
	v_cmp_gt_i32_e32 vcc, 64, v0
	s_and_saveexec_b64 s[12:13], vcc
	s_cbranch_execz .LBB0_757
	v_and_b32_e32 v2, 63, v6
	v_or_b32_e32 v9, s20, v2
	s_waitcnt lgkmcnt(0)
	s_cmp_lg_u64 s[8:9], 0
	s_movk_i32 s21, 0x104
	v_add_u32_e32 v4, s19, v0
	s_load_dwordx2 s[22:23], s[10:11], 0x0
	s_cselect_b64 s[14:15], -1, 0
	v_add_u32_e32 v7, -8, v0
	v_mul_lo_u32 v3, v0, s21
	v_lshlrev_b32_e32 v2, 2, v2
	v_ashrrev_i32_e32 v5, 31, v4
	s_lshl_b32 s21, s6, 2
	v_lshlrev_b32_e32 v0, 2, v9
	v_add3_u32 v8, v3, v2, 32
	v_lshl_add_u64 v[2:3], v[4:5], 2, s[8:9]
	v_mad_u64_u32 v[10:11], s[8:9], s21, v4, v[0:1]
	s_lshr_b64 s[8:9], s[6:7], 30
	s_nop 0
	v_mul_lo_u32 v0, s8, v4
	v_mul_lo_u32 v4, s21, v5
	v_add3_u32 v11, v0, v11, v4
	s_mov_b64 s[10:11], 0
	s_waitcnt lgkmcnt(0)
	v_lshl_add_u64 v[4:5], s[22:23], 0, v[10:11]
	s_lshl_b64 s[6:7], s[6:7], 5
	global_load_dword v200, v[4:5], off
	v_lshl_add_u64 v[4:5], v[4:5], 0, s[6:7]
	global_load_dword v201, v[4:5], off
	v_lshl_add_u64 v[4:5], v[4:5], 0, s[6:7]
	global_load_dword v202, v[4:5], off
	v_lshl_add_u64 v[4:5], v[4:5], 0, s[6:7]
	global_load_dword v203, v[4:5], off
	v_lshl_add_u64 v[4:5], v[4:5], 0, s[6:7]
	global_load_dword v204, v[4:5], off
	v_lshl_add_u64 v[4:5], v[4:5], 0, s[6:7]
	global_load_dword v205, v[4:5], off
	v_lshl_add_u64 v[4:5], v[4:5], 0, s[6:7]
	global_load_dword v206, v[4:5], off
	v_lshl_add_u64 v[4:5], v[4:5], 0, s[6:7]
	global_load_dword v207, v[4:5], off
	v_lshl_add_u64 v[4:5], v[4:5], 0, s[6:7]
	global_load_dword v216, v[4:5], off
	v_lshl_add_u64 v[4:5], v[4:5], 0, s[6:7]
	global_load_dword v217, v[4:5], off
	v_lshl_add_u64 v[4:5], v[4:5], 0, s[6:7]
	global_load_dword v218, v[4:5], off
	v_lshl_add_u64 v[4:5], v[4:5], 0, s[6:7]
	global_load_dword v219, v[4:5], off
	v_lshl_add_u64 v[4:5], v[4:5], 0, s[6:7]
	global_load_dword v220, v[4:5], off
	v_lshl_add_u64 v[4:5], v[4:5], 0, s[6:7]
	global_load_dword v221, v[4:5], off
	v_lshl_add_u64 v[4:5], v[4:5], 0, s[6:7]
	global_load_dword v222, v[4:5], off
	v_lshl_add_u64 v[4:5], v[4:5], 0, s[6:7]
	global_load_dword v223, v[4:5], off
	v_lshl_add_u64 v[4:5], v[4:5], 0, s[6:7]
	global_load_dword v20, v[4:5], off
	v_lshl_add_u64 v[4:5], v[4:5], 0, s[6:7]
	global_load_dword v21, v[4:5], off
	v_lshl_add_u64 v[4:5], v[4:5], 0, s[6:7]
	global_load_dword v22, v[4:5], off
	v_lshl_add_u64 v[4:5], v[4:5], 0, s[6:7]
	global_load_dword v23, v[4:5], off
	v_lshl_add_u64 v[4:5], v[4:5], 0, s[6:7]
	global_load_dword v24, v[4:5], off
	v_lshl_add_u64 v[4:5], v[4:5], 0, s[6:7]
	global_load_dword v25, v[4:5], off
	v_lshl_add_u64 v[4:5], v[4:5], 0, s[6:7]
	global_load_dword v26, v[4:5], off
	v_lshl_add_u64 v[4:5], v[4:5], 0, s[6:7]
	global_load_dword v27, v[4:5], off
	v_lshl_add_u64 v[4:5], v[4:5], 0, s[6:7]
	global_load_dword v28, v[4:5], off
	v_lshl_add_u64 v[4:5], v[4:5], 0, s[6:7]
	global_load_dword v29, v[4:5], off
	v_lshl_add_u64 v[4:5], v[4:5], 0, s[6:7]
	global_load_dword v30, v[4:5], off
	v_lshl_add_u64 v[4:5], v[4:5], 0, s[6:7]
	global_load_dword v31, v[4:5], off
	v_lshl_add_u64 v[4:5], v[4:5], 0, s[6:7]
	global_load_dword v32, v[4:5], off
	v_lshl_add_u64 v[4:5], v[4:5], 0, s[6:7]
	global_load_dword v33, v[4:5], off
	v_lshl_add_u64 v[4:5], v[4:5], 0, s[6:7]
	global_load_dword v34, v[4:5], off
	v_lshl_add_u64 v[4:5], v[4:5], 0, s[6:7]
	global_load_dword v35, v[4:5], off
	s_andn2_b64 vcc, exec, s[14:15]
	s_cbranch_vccnz .Lmy_xpe_store
	global_load_dword v208, v[2:3], off
	v_lshl_add_u64 v[2:3], v[2:3], 0, 32
	global_load_dword v209, v[2:3], off
	v_lshl_add_u64 v[2:3], v[2:3], 0, 32
	global_load_dword v210, v[2:3], off
	v_lshl_add_u64 v[2:3], v[2:3], 0, 32
	global_load_dword v211, v[2:3], off
	v_lshl_add_u64 v[2:3], v[2:3], 0, 32
	global_load_dword v212, v[2:3], off
	v_lshl_add_u64 v[2:3], v[2:3], 0, 32
	global_load_dword v213, v[2:3], off
	v_lshl_add_u64 v[2:3], v[2:3], 0, 32
	global_load_dword v214, v[2:3], off
	v_lshl_add_u64 v[2:3], v[2:3], 0, 32
	global_load_dword v215, v[2:3], off
	v_lshl_add_u64 v[2:3], v[2:3], 0, 32
	global_load_dword v224, v[2:3], off
	v_lshl_add_u64 v[2:3], v[2:3], 0, 32
	global_load_dword v225, v[2:3], off
	v_lshl_add_u64 v[2:3], v[2:3], 0, 32
	global_load_dword v226, v[2:3], off
	v_lshl_add_u64 v[2:3], v[2:3], 0, 32
	global_load_dword v227, v[2:3], off
	v_lshl_add_u64 v[2:3], v[2:3], 0, 32
	global_load_dword v228, v[2:3], off
	v_lshl_add_u64 v[2:3], v[2:3], 0, 32
	global_load_dword v229, v[2:3], off
	v_lshl_add_u64 v[2:3], v[2:3], 0, 32
	global_load_dword v230, v[2:3], off
	v_lshl_add_u64 v[2:3], v[2:3], 0, 32
	global_load_dword v231, v[2:3], off
	v_lshl_add_u64 v[2:3], v[2:3], 0, 32
	global_load_dword v36, v[2:3], off
	v_lshl_add_u64 v[2:3], v[2:3], 0, 32
	global_load_dword v37, v[2:3], off
	v_lshl_add_u64 v[2:3], v[2:3], 0, 32
	global_load_dword v38, v[2:3], off
	v_lshl_add_u64 v[2:3], v[2:3], 0, 32
	global_load_dword v39, v[2:3], off
	v_lshl_add_u64 v[2:3], v[2:3], 0, 32
	global_load_dword v40, v[2:3], off
	v_lshl_add_u64 v[2:3], v[2:3], 0, 32
	global_load_dword v41, v[2:3], off
	v_lshl_add_u64 v[2:3], v[2:3], 0, 32
	global_load_dword v42, v[2:3], off
	v_lshl_add_u64 v[2:3], v[2:3], 0, 32
	global_load_dword v43, v[2:3], off
	v_lshl_add_u64 v[2:3], v[2:3], 0, 32
	global_load_dword v44, v[2:3], off
	v_lshl_add_u64 v[2:3], v[2:3], 0, 32
	global_load_dword v45, v[2:3], off
	v_lshl_add_u64 v[2:3], v[2:3], 0, 32
	global_load_dword v46, v[2:3], off
	v_lshl_add_u64 v[2:3], v[2:3], 0, 32
	global_load_dword v47, v[2:3], off
	v_lshl_add_u64 v[2:3], v[2:3], 0, 32
	global_load_dword v48, v[2:3], off
	v_lshl_add_u64 v[2:3], v[2:3], 0, 32
	global_load_dword v49, v[2:3], off
	v_lshl_add_u64 v[2:3], v[2:3], 0, 32
	global_load_dword v50, v[2:3], off
	v_lshl_add_u64 v[2:3], v[2:3], 0, 32
	global_load_dword v51, v[2:3], off
	s_waitcnt vmcnt(0)
	v_mul_f32_e32 v200, v200, v208
	v_mul_f32_e32 v201, v201, v209
	v_mul_f32_e32 v202, v202, v210
	v_mul_f32_e32 v203, v203, v211
	v_mul_f32_e32 v204, v204, v212
	v_mul_f32_e32 v205, v205, v213
	v_mul_f32_e32 v206, v206, v214
	v_mul_f32_e32 v207, v207, v215
	v_mul_f32_e32 v216, v216, v224
	v_mul_f32_e32 v217, v217, v225
	v_mul_f32_e32 v218, v218, v226
	v_mul_f32_e32 v219, v219, v227
	v_mul_f32_e32 v220, v220, v228
	v_mul_f32_e32 v221, v221, v229
	v_mul_f32_e32 v222, v222, v230
	v_mul_f32_e32 v223, v223, v231
	v_mul_f32_e32 v20, v20, v36
	v_mul_f32_e32 v21, v21, v37
	v_mul_f32_e32 v22, v22, v38
	v_mul_f32_e32 v23, v23, v39
	v_mul_f32_e32 v24, v24, v40
	v_mul_f32_e32 v25, v25, v41
	v_mul_f32_e32 v26, v26, v42
	v_mul_f32_e32 v27, v27, v43
	v_mul_f32_e32 v28, v28, v44
	v_mul_f32_e32 v29, v29, v45
	v_mul_f32_e32 v30, v30, v46
	v_mul_f32_e32 v31, v31, v47
	v_mul_f32_e32 v32, v32, v48
	v_mul_f32_e32 v33, v33, v49
	v_mul_f32_e32 v34, v34, v50
	v_mul_f32_e32 v35, v35, v51
; DI void xpose_tile(int wv0, PP p, int jt, unsigned char* smem) {
;     ...
;   for (int kk = ty; kk < 64; kk += 8) {
;     float val = 0.f;
;     if (sc >= 0) val = src[(size_t)(k0 + kk) * Nsrc + sc];
;     if (scl) val *= scl[k0 + kk];
;     tile[kk * 65 + tx] = val;
;   }
;   __syncthreads();
;   {
;     const int n = tid >> 3, kc = tid & 7;
;     uint4 o;
;     o.x = pk2(tile[(kc * 8 + 0) * 65 + n], tile[(kc * 8 + 1) * 65 + n]);
;     o.y = pk2(tile[(kc * 8 + 2) * 65 + n], tile[(kc * 8 + 3) * 65 + n]);
;     o.z = pk2(tile[(kc * 8 + 4) * 65 + n], tile[(kc * 8 + 5) * 65 + n]);
;     o.w = pk2(tile[(kc * 8 + 6) * 65 + n], tile[(kc * 8 + 7) * 65 + n]);
;     const int drow = rowil < 0 ? (n0 + n) : (((n0 + n) >> 7) * 256 + ((n0 + n) & 127) + rowil);
;     *(uint4*)(dst + (size_t)drow * K + k0 + kc * 8) = o;
;   }
;   __syncthreads();
.Lmy_xpe_store:
	s_waitcnt vmcnt(0)
	ds_write_b32 v8, v200
	ds_write_b32 v8, v201 offset:2080
	ds_write_b32 v8, v202 offset:4160
	ds_write_b32 v8, v203 offset:6240
	ds_write_b32 v8, v204 offset:8320
	ds_write_b32 v8, v205 offset:10400
	ds_write_b32 v8, v206 offset:12480
	ds_write_b32 v8, v207 offset:14560
	ds_write_b32 v8, v216 offset:16640
	ds_write_b32 v8, v217 offset:18720
	ds_write_b32 v8, v218 offset:20800
	ds_write_b32 v8, v219 offset:22880
	ds_write_b32 v8, v220 offset:24960
	ds_write_b32 v8, v221 offset:27040
	ds_write_b32 v8, v222 offset:29120
	ds_write_b32 v8, v223 offset:31200
	ds_write_b32 v8, v20 offset:33280
	ds_write_b32 v8, v21 offset:35360
	ds_write_b32 v8, v22 offset:37440
	ds_write_b32 v8, v23 offset:39520
	ds_write_b32 v8, v24 offset:41600
	ds_write_b32 v8, v25 offset:43680
	ds_write_b32 v8, v26 offset:45760
	ds_write_b32 v8, v27 offset:47840
	ds_write_b32 v8, v28 offset:49920
	ds_write_b32 v8, v29 offset:52000
	ds_write_b32 v8, v30 offset:54080
	ds_write_b32 v8, v31 offset:56160
	ds_write_b32 v8, v32 offset:58240
	ds_write_b32 v8, v33 offset:60320
	ds_write_b32 v8, v34 offset:62400
	ds_write_b32 v8, v35 offset:64480
.LBB0_757:
	s_or_b64 exec, exec, s[12:13]
	v_lshlrev_b32_e32 v2, 3, v6
	v_ashrrev_i32_e32 v0, 3, v6
	v_and_b32_e32 v10, 56, v2
	v_mul_u32_u24_e32 v2, 0x104, v10
	v_lshlrev_b32_e32 v3, 2, v0
	v_add3_u32 v4, 32, v2, v3
	s_waitcnt lgkmcnt(0)
	s_barrier
	v_add_u32_e32 v235, 0, v4
	v_add_u32_e32 v232, 0x4100, v4
	ds_read2_b32 v[52:53], v232 offset1:65
	ds_read2_b32 v[54:55], v232 offset0:130 offset1:195
	v_add_u32_e32 v232, 0x400, v232
	ds_read2_b32 v[56:57], v232 offset0:4 offset1:69
	ds_read2_b32 v[58:59], v232 offset0:134 offset1:199
	v_add_u32_e32 v233, 0x8200, v4
	ds_read2_b32 v[60:61], v233 offset1:65
	ds_read2_b32 v[62:63], v233 offset0:130 offset1:195
	v_add_u32_e32 v233, 0x400, v233
	ds_read2_b32 v[64:65], v233 offset0:4 offset1:69
	ds_read2_b32 v[66:67], v233 offset0:134 offset1:199
	ds_read2_b32 v[6:7], v4 offset1:65
	ds_read2_b32 v[2:3], v4 offset0:130 offset1:195
	v_add_u32_e32 v4, 0x400, v4
	v_add_u32_e32 v0, s20, v0
	ds_read2_b32 v[8:9], v4 offset0:4 offset1:69
	ds_read2_b32 v[4:5], v4 offset0:134 offset1:199
	v_lshlrev_b32_e32 v11, 1, v0
	v_and_b32_e32 v11, 0xffffff00, v11
	v_and_b32_e32 v12, 0x7f, v0
	v_add3_u32 v11, v12, s18, v11
	v_cndmask_b32_e64 v0, v11, v0, s[2:3]
	s_waitcnt lgkmcnt(2)
	v_cvt_pk_bf16_f32 v3, v2, v3
	v_cvt_pk_bf16_f32 v2, v6, v7
	v_mad_u64_u32 v[6:7], s[2:3], v0, s17, 0
	s_waitcnt lgkmcnt(0)
	v_cvt_pk_bf16_f32 v5, v4, v5
	v_cvt_pk_bf16_f32 v4, v8, v9
	v_ashrrev_i32_e32 v8, 31, v0
	v_mov_b32_e32 v0, v7
	v_mad_u64_u32 v[8:9], s[2:3], v8, s17, v[0:1]
	v_mov_b32_e32 v7, v8
	v_lshl_add_u64 v[6:7], v[6:7], 1, s[4:5]
	s_lshl_b32 s88, s19, 1
	v_lshl_add_u64 v[6:7], v[6:7], 0, s[88:89]
	v_lshlrev_b32_e32 v0, 1, v10
	v_lshl_add_u64 v[6:7], v[6:7], 0, v[0:1]
	global_store_dwordx4 v[6:7], v[2:5], off
	v_add_u32_e32 v234, 0xc300, v235
	ds_read2_b32 v[68:69], v234 offset1:65
	ds_read2_b32 v[70:71], v234 offset0:130 offset1:195
	v_add_u32_e32 v234, 0x400, v234
	ds_read2_b32 v[72:73], v234 offset0:4 offset1:69
	ds_read2_b32 v[74:75], v234 offset0:134 offset1:199
	s_waitcnt lgkmcnt(0)
	v_cvt_pk_bf16_f32 v52, v52, v53
	v_cvt_pk_bf16_f32 v53, v54, v55
	v_cvt_pk_bf16_f32 v54, v56, v57
	v_cvt_pk_bf16_f32 v55, v58, v59
	global_store_dwordx4 v[6:7], v[52:55], off offset:128
	v_cvt_pk_bf16_f32 v60, v60, v61
	v_cvt_pk_bf16_f32 v61, v62, v63
	v_cvt_pk_bf16_f32 v62, v64, v65
	v_cvt_pk_bf16_f32 v63, v66, v67
	global_store_dwordx4 v[6:7], v[60:63], off offset:256
	v_cvt_pk_bf16_f32 v68, v68, v69
	v_cvt_pk_bf16_f32 v69, v70, v71
	v_cvt_pk_bf16_f32 v70, v72, v73
	v_cvt_pk_bf16_f32 v71, v74, v75
	global_store_dwordx4 v[6:7], v[68:71], off offset:384
	s_barrier
	s_mov_b64 s[2:3], 0

; DI void nsa_item(int wv0, PP p, int item, unsigned char* smem) {
;     ...
; #pragma unroll
;     for (int qt = 0; qt < 2; ++qt) {
;       const float gt = NGb[ngoff + qt * 3 + 0];
; #pragma unroll
;       for (int dt = 0; dt < 4; ++dt) {
;         float4 o = make_float4(O[qt][dt][0] * gt, O[qt][dt][1] * gt, O[qt][dt][2] * gt, O[qt][dt][3] * gt);
;         *(float4*)(ACCb + (aoff + qt * 64 + 16 * dt)) = o;
;       }
;     }
;   }
;   __syncthreads();
;   u64 mlo = 0, mhi = 0, wlo = 0, whi = 0;
;   if (i < 16) {
;     mlo = (1ull << (i + 1)) - 1ull;
;     wlo = mlo;
;   } else {
;     const bool v0 = lane <= i, v1 = (lane + 64) <= i;
;     const bool f0 = (lane == 0) || (lane == i) || (lane == i - 1);
;     const bool f1 = (lane + 64 == i) || (lane + 64 == i - 1);
;     const u64 ltm = (1ull << lane) - 1ull;
.LBB0_813:
	s_mul_i32 s2, s40, 12
	v_readlane_b32 s3, v247, 49
	s_add_i32 s2, s2, s3
	v_mov_b32_e32 v2, s2
	v_mad_u64_u32 v[142:143], s[2:3], v74, 24, v[2:3]
	v_mov_b32_e32 v143, v1
	v_lshl_add_u64 v[2:3], v[142:143], 2, s[94:95]
	global_load_dword v16, v[2:3], off
	v_readlane_b32 s2, v247, 5
	v_readlane_b32 s3, v247, 6
	s_load_dwordx2 s[2:3], s[2:3], 0xc0
	v_or_b32_e32 v138, v72, v153
	v_mov_b32_e32 v139, v1
	v_mov_b32_e32 v3, v1
	v_add_u32_e32 v2, 3, v142
	s_waitcnt lgkmcnt(0)
	v_lshl_add_u64 v[140:141], v[138:139], 2, s[2:3]
	s_waitcnt vmcnt(1)
	v_lshl_add_u64 v[34:35], v[2:3], 2, s[94:95]
	global_load_dword v200, v[34:35], off
	s_mov_b64 s[2:3], -1
	s_cmpk_lt_i32 s88, 0x70
	v_cmp_eq_u32_e32 vcc, 0, v71
	s_waitcnt vmcnt(0)
	v_pk_mul_f32 v[2:3], v[54:55], v[16:17] op_sel_hi:[1,0]
	v_pk_mul_f32 v[4:5], v[56:57], v[16:17] op_sel_hi:[1,0]
	v_pk_mul_f32 v[6:7], v[50:51], v[16:17] op_sel_hi:[1,0]
	v_pk_mul_f32 v[8:9], v[52:53], v[16:17] op_sel_hi:[1,0]
	v_pk_mul_f32 v[10:11], v[46:47], v[16:17] op_sel_hi:[1,0]
	v_pk_mul_f32 v[12:13], v[48:49], v[16:17] op_sel_hi:[1,0]
	v_pk_mul_f32 v[14:15], v[42:43], v[16:17] op_sel_hi:[1,0]
	v_pk_mul_f32 v[16:17], v[44:45], v[16:17] op_sel_hi:[1,0]
	v_mov_b64_e32 v[218:219], v[2:3]
	v_mov_b64_e32 v[220:221], v[4:5]
	v_mov_b64_e32 v[222:223], v[6:7]
	v_mov_b64_e32 v[224:225], v[8:9]
	v_mov_b64_e32 v[226:227], v[10:11]
	v_mov_b64_e32 v[228:229], v[12:13]
	v_mov_b64_e32 v[230:231], v[14:15]
	v_mov_b64_e32 v[232:233], v[16:17]
	v_pk_mul_f32 v[2:3], v[30:31], v[200:201] op_sel_hi:[1,0]
	v_pk_mul_f32 v[4:5], v[32:33], v[200:201] op_sel_hi:[1,0]
	v_pk_mul_f32 v[6:7], v[26:27], v[200:201] op_sel_hi:[1,0]
	v_pk_mul_f32 v[8:9], v[28:29], v[200:201] op_sel_hi:[1,0]
	v_pk_mul_f32 v[10:11], v[22:23], v[200:201] op_sel_hi:[1,0]
	v_pk_mul_f32 v[12:13], v[24:25], v[200:201] op_sel_hi:[1,0]
	v_pk_mul_f32 v[14:15], v[18:19], v[200:201] op_sel_hi:[1,0]
	v_pk_mul_f32 v[16:17], v[20:21], v[200:201] op_sel_hi:[1,0]
	v_mov_b64_e32 v[234:235], v[2:3]
	v_mov_b64_e32 v[236:237], v[4:5]
	v_mov_b64_e32 v[238:239], v[6:7]
	v_mov_b64_e32 v[240:241], v[8:9]
	v_mov_b64_e32 v[242:243], v[10:11]
	v_mov_b64_e32 v[244:245], v[12:13]
	v_mov_b64_e32 v[248:249], v[14:15]
	v_mov_b64_e32 v[250:251], v[16:17]
	v_lshlrev_b32_e32 v206, 1, v0
	global_load_dword v202, v206, s[86:87]
	global_load_dword v203, v206, s[86:87] offset:128
	s_lshl_b32 s32, s84, 20
	v_readlane_b32 s4, v247, 59
	v_readlane_b32 s5, v247, 60
	s_nop 1
	s_add_u32 s4, s4, s32
	s_addc_u32 s5, s5, 0
	v_lshl_or_b32 v207, v70, 14, v68
	s_nop 3
	global_load_dword v204, v152, s[4:5]
	v_readlane_b32 s4, v247, 61
	v_readlane_b32 s5, v247, 62
	s_nop 1
	s_add_u32 s4, s4, s32
	s_addc_u32 s5, s5, 0
	s_nop 4
	global_load_dword v205, v207, s[4:5]
	s_cmpk_lt_i32 s88, 0x70
	s_barrier
	s_cbranch_scc0 .LBB0_820
	v_cmp_eq_u32_e64 s[10:11], s33, v71
	s_sub_i32 s14, 0x7e, s88
	s_or_b64 s[12:13], vcc, s[10:11]
	v_cmp_eq_u32_e64 s[10:11], s14, v71
	v_or_b32_e32 v2, 64, v71
	s_or_b64 s[10:11], s[12:13], s[10:11]
	v_cndmask_b32_e64 v4, 0, v149, s[10:11]
	v_cmp_eq_u32_e64 s[10:11], s33, v2
	v_cmp_eq_u32_e64 s[12:13], s14, v2
	s_or_b64 s[10:11], s[10:11], s[12:13]
	v_cmp_lt_i32_e64 s[6:7], s33, v2
	v_cmp_ge_i32_e64 s[8:9], s33, v2
	v_cndmask_b32_e64 v5, 0, v149, s[10:11]
	v_lshlrev_b64 v[2:3], v71, -1
	v_readlane_b32 s10, v246, 7
	v_cmp_lt_i32_e64 s[2:3], s33, v71
	v_cmp_ge_i32_e64 s[4:5], s33, v71
	v_not_b32_e32 v3, v3
	v_not_b32_e32 v2, v2
	v_lshl_add_u32 v6, v71, 2, s10
	s_mov_b64 s[20:21], 0
	s_mov_b32 s24, 8
	v_readlane_b32 s25, v246, 6
	s_mov_b64 s[22:23], 0
	s_branch .LBB0_816

; #define ISSUE_TILE(RK, RV, T, LDV)                                                   \
;   {                                                                                  \
;     pk0 = BLOAD(RK, koff, (T)*8192);                                                 \
;     pv0 = BLOAD(RV, ((LDV) == 512) ? voffc : voffs, (T)*128);                        \
;   }
; DI void nsa_item(int wv0, PP p, int item, unsigned char* smem) {
;     ...
;       int jc = next_bit(blo, bhi, 0);
;       int j1 = next_bit(blo, bhi, jc + 1);
;       ISSUE_TILE(rK, rV, jc, S_)
;       COMMIT_BUF(0)
;       if (j1 >= 0) {
;         ISSUE_TILE(rK, rV, j1, S_)
;         COMMIT_BUF(1)
;       }
;       __syncthreads();
.LBB0_864:
	s_lshl_b32 s2, s85, 13
	s_lshl_b32 s3, s85, 7
	s_mov_b32 s74, s70
	s_mov_b32 s75, s71
	buffer_load_dwordx4 v[24:27], v152, s[68:71], s2 offen
	buffer_load_dwordx4 v[62:65], v143, s[72:75], s3 offen
	s_cmp_gt_i32 s42, -1
	s_cselect_b64 s[2:3], -1, 0
	s_cmp_lt_i32 s42, 0
	s_cbranch_scc1 .Lmy_pre_one
	s_lshl_b32 s5, s42, 13
	s_lshl_b32 s4, s42, 7
	buffer_load_dwordx4 v[202:205], v152, s[68:71], s5 offen
	buffer_load_dwordx4 v[206:209], v143, s[72:75], s4 offen
	s_waitcnt vmcnt(3)
	ds_write_b128 v154, v[24:27]
	s_waitcnt vmcnt(2)
	ds_write_b128 v154, v[62:65] offset:9216
	s_waitcnt vmcnt(1)
	ds_write_b128 v154, v[202:205] offset:18432
	s_waitcnt vmcnt(0)
	ds_write_b128 v154, v[206:209] offset:27648
	s_branch .LBB0_866
.Lmy_pre_one:
	s_waitcnt vmcnt(1)
	ds_write_b128 v154, v[24:27]
	s_waitcnt vmcnt(0)
	ds_write_b128 v154, v[62:65] offset:9216
